# plus LDS-staged tail K loops for phases 1 and 9 (all GEMM tails except phase 12)
# baseline (speedup 1.0000x reference)
; DI f32x16 mfma32(bf16x8 a, bf16x8 b, f32x16 c) { return __builtin_amdgcn_mfma_f32_32x32x16_bf16(a, b, c, 0, 0, 0); }
; DI f32x16 zero16() { f32x16 z; for (int i = 0; i < 16; ++i) z[i] = 0.f; return z; }
; DI int opaque_tid() { int t = threadIdx.x; asm volatile("" : "+v"(t)); return t; }
; template <int EPI, int K, int LNI>
; DI void gemm_tail_unit(const Params& p, const bf16_t* __restrict__ A, const bf16_t* __restrict__ Bt, const int un, float* s_aux) {
;     const int tid = opaque_tid(), lane = tid & 63, w = tid >> 6, r = lane & 31, h = lane >> 5;
;     constexpr int ROW0 = 32768, KS = K / 8;
;     const int col0 = un * 64;
;     if (EPI == EPI_E5B) {
;         if (tid < 64) {
;             const int hd = col0 >> 9;
;             const float* pp = (const float*)((unsigned char*)p.out + OFFO_PART) + (size_t)(ROW0 + tid) * 256 + hd * 64;
;             float sacc = 0.f;
; #pragma unroll
;             for (int i = 0; i < 16; ++i) { const f32x4 v = *(const f32x4*)(pp + i * 4); sacc += (v[0] + v[1]) + (v[2] + v[3]); }
;             s_aux[tid] = __frsqrt_rn(sacc * (1.0f / 512.0f) + 1e-6f);
;         }
;     }
;     f32x16 acc[2][2];
;     acc[0][0] = zero16(); acc[0][1] = zero16(); acc[1][0] = zero16(); acc[1][1] = zero16();
;     const bf16_t* ap = A + (size_t)(ROW0 + r) * K + w * KS + h * 8;
;     const bf16_t* bp = Bt + (size_t)(col0 + r) * K + w * KS + h * 8;
; #pragma unroll 8
;     for (int s = 0; s < KS / 16; ++s) {
;         const bf16x8 a0 = *(const bf16x8*)(ap + s * 16), a1 = *(const bf16x8*)(ap + (size_t)32 * K + s * 16);
;         const bf16x8 b0 = *(const bf16x8*)(bp + s * 16), b1 = *(const bf16x8*)(bp + (size_t)32 * K + s * 16);
;         acc[0][0] = mfma32(a0, b0, acc[0][0]); acc[0][1] = mfma32(a0, b1, acc[0][1]);
;         acc[1][0] = mfma32(a1, b0, acc[1][0]); acc[1][1] = mfma32(a1, b1, acc[1][1]);
;     }
.LBB0_402:
	v_mov_b32_e32 v67, v210
	s_ashr_i32 s19, s18, 3
	v_ashrrev_i32_e32 v70, 6, v67
	v_and_b32_e32 v66, 31, v67
	v_lshlrev_b32_e32 v2, 7, v70
	v_lshlrev_b32_e32 v64, 11, v66
	v_ashrrev_i32_e32 v3, 31, v2
	v_bfe_u32 v68, v67, 5, 1
	v_lshl_add_u64 v[0:1], s[40:41], 0, v[64:65]
	v_lshlrev_b64 v[4:5], 1, v[2:3]
	v_lshl_add_u64 v[0:1], v[0:1], 0, v[4:5]
	v_lshlrev_b32_e32 v64, 4, v68
	v_lshl_add_u64 v[12:13], v[0:1], 0, v[64:65]
	v_add_u32_e32 v0, s3, v66
	v_ashrrev_i32_e32 v1, 31, v0
	v_lshlrev_b64 v[6:7], 11, v[0:1]
	v_add_co_u32_e32 v0, vcc, s11, v12
	v_lshl_add_u64 v[6:7], s[56:57], 0, v[6:7]
	s_nop 0
	v_addc_co_u32_e32 v1, vcc, 0, v13, vcc
	s_nop 0
	v_readfirstlane_b32 s88, v0
	v_readfirstlane_b32 s89, v1
	v_lshl_add_u64 v[4:5], v[6:7], 0, v[4:5]
	v_lshl_add_u64 v[108:109], v[4:5], 0, v[64:65]
	v_add_co_u32_e32 v112, vcc, s13, v108
	v_lshl_add_u64 v[110:111], v[12:13], 0, s[0:1]
	s_nop 0
	v_addc_co_u32_e32 v113, vcc, 0, v109, vcc
	s_nop 0
	v_readfirstlane_b32 s90, v108
	v_readfirstlane_b32 s91, v109
	v_add_co_u32_e32 v114, vcc, s12, v12
	v_and_b32_e32 v64, 63, v67
	s_nop 0
	v_addc_co_u32_e32 v115, vcc, 0, v13, vcc
	v_lshl_add_u32 v69, v64, 2, 0
	v_lshl_add_u32 v64, v70, 14, v69
	s_cmp_eq_u32 s19, 2
	s_cselect_b32 s20, 0, 0x800
	s_cmp_eq_u32 s19, 3
	s_cselect_b32 s4, s15, 0x600
	s_cmp_lg_u32 s19, 1
	s_cselect_b32 s4, s4, 0x200
	s_cmpk_gt_u32 s3, 0x1ff
	s_cselect_b32 s21, s4, 0
	s_cmp_lt_i32 s19, 5
	s_nop 11
	s_nop 6
	s_nop 5
	v_and_b32_e32 v244, 63, v210
	v_lshrrev_b32_e32 v245, 3, v244
	v_and_b32_e32 v249, 7, v244
	v_lshlrev_b32_e32 v247, 11, v245
	v_lshl_add_u32 v247, v249, 4, v247
	v_lshrrev_b32_e32 v248, 6, v210
	v_lshlrev_b32_e32 v248, 14, v248
	v_mul_u32_u24_e32 v245, 0x90, v245
	v_lshl_add_u32 v245, v249, 4, v245
	v_add_u32_e32 v245, v245, v248
	v_and_b32_e32 v246, 31, v210
	v_mul_u32_u24_e32 v246, 0x90, v246
	v_bfe_u32 v249, v210, 5, 1
	v_lshl_add_u32 v246, v249, 4, v246
	v_add_u32_e32 v246, v246, v248
	global_load_dwordx4 v[72:75], v247, s[88:89]
	s_add_u32 s92, s88, 0x4000
	s_addc_u32 s93, s89, 0
	s_nop 0
	global_load_dwordx4 v[76:79], v247, s[92:93]
	s_add_u32 s94, s88, 0x8000
	s_addc_u32 s95, s89, 0
	s_nop 0
	global_load_dwordx4 v[80:83], v247, s[94:95]
	s_add_u32 s92, s88, 0xc000
	s_addc_u32 s93, s89, 0
	s_nop 0
	global_load_dwordx4 v[84:87], v247, s[92:93]
	s_add_u32 s94, s88, 0x10000
	s_addc_u32 s95, s89, 0
	s_nop 0
	global_load_dwordx4 v[88:91], v247, s[94:95]
	s_add_u32 s92, s88, 0x14000
	s_addc_u32 s93, s89, 0
	s_nop 0
	global_load_dwordx4 v[92:95], v247, s[92:93]
	s_add_u32 s94, s88, 0x18000
	s_addc_u32 s95, s89, 0
	s_nop 0
	global_load_dwordx4 v[96:99], v247, s[94:95]
	s_add_u32 s92, s88, 0x1c000
	s_addc_u32 s93, s89, 0
	s_nop 0
	global_load_dwordx4 v[100:103], v247, s[92:93]
	global_load_dwordx4 v[104:107], v247, s[90:91]
	s_add_u32 s94, s90, 0x4000
	s_addc_u32 s95, s91, 0
	s_nop 0
	global_load_dwordx4 v[116:119], v247, s[94:95]
	s_add_u32 s92, s90, 0x8000
	s_addc_u32 s93, s91, 0
	s_nop 0
	global_load_dwordx4 v[120:123], v247, s[92:93]
	s_add_u32 s94, s90, 0xc000
	s_addc_u32 s95, s91, 0
	s_nop 0
	global_load_dwordx4 v[124:127], v247, s[94:95]
	s_add_u32 s92, s90, 0x10000
	s_addc_u32 s93, s91, 0
	s_nop 0
	global_load_dwordx4 v[128:131], v247, s[92:93]
	s_add_u32 s94, s90, 0x14000
	s_addc_u32 s95, s91, 0
	s_nop 0
	global_load_dwordx4 v[132:135], v247, s[94:95]
	s_add_u32 s92, s90, 0x18000
	s_addc_u32 s93, s91, 0
	s_nop 0
	global_load_dwordx4 v[136:139], v247, s[92:93]
	s_add_u32 s94, s90, 0x1c000
	s_addc_u32 s95, s91, 0
	s_nop 0
	global_load_dwordx4 v[140:143], v247, s[94:95]
	global_load_dwordx4 v[144:147], v247, s[88:89] offset:128
	s_add_u32 s92, s88, 0x4000
	s_addc_u32 s93, s89, 0
	s_nop 0
	global_load_dwordx4 v[148:151], v247, s[92:93] offset:128
	s_add_u32 s94, s88, 0x8000
	s_addc_u32 s95, s89, 0
	s_nop 0
	global_load_dwordx4 v[152:155], v247, s[94:95] offset:128
	s_add_u32 s92, s88, 0xc000
	s_addc_u32 s93, s89, 0
	s_nop 0
	global_load_dwordx4 v[156:159], v247, s[92:93] offset:128
	s_add_u32 s94, s88, 0x10000
	s_addc_u32 s95, s89, 0
	s_nop 0
	global_load_dwordx4 v[160:163], v247, s[94:95] offset:128
	s_add_u32 s92, s88, 0x14000
	s_addc_u32 s93, s89, 0
	s_nop 0
	global_load_dwordx4 v[164:167], v247, s[92:93] offset:128
	s_add_u32 s94, s88, 0x18000
	s_addc_u32 s95, s89, 0
	s_nop 0
	global_load_dwordx4 v[168:171], v247, s[94:95] offset:128
	s_add_u32 s92, s88, 0x1c000
	s_addc_u32 s93, s89, 0
	s_nop 0
	global_load_dwordx4 v[172:175], v247, s[92:93] offset:128
	global_load_dwordx4 v[176:179], v247, s[90:91] offset:128
	s_add_u32 s94, s90, 0x4000
	s_addc_u32 s95, s91, 0
	s_nop 0
	global_load_dwordx4 v[180:183], v247, s[94:95] offset:128
	s_add_u32 s92, s90, 0x8000
	s_addc_u32 s93, s91, 0
	s_nop 0
	global_load_dwordx4 v[184:187], v247, s[92:93] offset:128
	s_add_u32 s94, s90, 0xc000
	s_addc_u32 s95, s91, 0
	s_nop 0
	global_load_dwordx4 v[188:191], v247, s[94:95] offset:128
	s_add_u32 s92, s90, 0x10000
	s_addc_u32 s93, s91, 0
	s_nop 0
	global_load_dwordx4 v[192:195], v247, s[92:93] offset:128
	s_add_u32 s94, s90, 0x14000
	s_addc_u32 s95, s91, 0
	s_nop 0
	global_load_dwordx4 v[196:199], v247, s[94:95] offset:128
	s_add_u32 s92, s90, 0x18000
	s_addc_u32 s93, s91, 0
	s_nop 0
	global_load_dwordx4 v[200:203], v247, s[92:93] offset:128
	s_add_u32 s94, s90, 0x1c000
	s_addc_u32 s95, s91, 0
	s_nop 0
	global_load_dwordx4 v[204:207], v247, s[94:95] offset:128
	s_waitcnt vmcnt(24) lgkmcnt(0)
	ds_write_b128 v245, v[72:75]
	ds_write_b128 v245, v[76:79] offset:1152
	ds_write_b128 v245, v[80:83] offset:2304
	ds_write_b128 v245, v[84:87] offset:3456
	ds_write_b128 v245, v[88:91] offset:4608
	ds_write_b128 v245, v[92:95] offset:5760
	ds_write_b128 v245, v[96:99] offset:6912
	ds_write_b128 v245, v[100:103] offset:8064
	s_waitcnt lgkmcnt(0)
; DI f32x16 mfma32(bf16x8 a, bf16x8 b, f32x16 c) { return __builtin_amdgcn_mfma_f32_32x32x16_bf16(a, b, c, 0, 0, 0); }
; template <int EPI, int K, int LNI>
; DI void gemm_tail_unit(const Params& p, const bf16_t* __restrict__ A, const bf16_t* __restrict__ Bt, const int un, float* s_aux) {
;     ...
; #pragma unroll 8
;     for (int s = 0; s < KS / 16; ++s) {
;         const bf16x8 a0 = *(const bf16x8*)(ap + s * 16), a1 = *(const bf16x8*)(ap + (size_t)32 * K + s * 16);
;         const bf16x8 b0 = *(const bf16x8*)(bp + s * 16), b1 = *(const bf16x8*)(bp + (size_t)32 * K + s * 16);
;         acc[0][0] = mfma32(a0, b0, acc[0][0]); acc[0][1] = mfma32(a0, b1, acc[0][1]);
;         acc[1][0] = mfma32(a1, b0, acc[1][0]); acc[1][1] = mfma32(a1, b1, acc[1][1]);
;     }
	ds_read_b128 v[72:75], v246
	ds_read_b128 v[76:79], v246 offset:32
	ds_read_b128 v[80:83], v246 offset:64
	ds_read_b128 v[84:87], v246 offset:96
	ds_read_b128 v[88:91], v246 offset:4608
	ds_read_b128 v[92:95], v246 offset:4640
	ds_read_b128 v[96:99], v246 offset:4672
	ds_read_b128 v[100:103], v246 offset:4704
	s_waitcnt vmcnt(16) lgkmcnt(0)
	ds_write_b128 v245, v[104:107]
	ds_write_b128 v245, v[116:119] offset:1152
	ds_write_b128 v245, v[120:123] offset:2304
	ds_write_b128 v245, v[124:127] offset:3456
	ds_write_b128 v245, v[128:131] offset:4608
	ds_write_b128 v245, v[132:135] offset:5760
	ds_write_b128 v245, v[136:139] offset:6912
	ds_write_b128 v245, v[140:143] offset:8064
	s_waitcnt lgkmcnt(0)
	ds_read_b128 v[104:107], v246
	ds_read_b128 v[116:119], v246 offset:32
	ds_read_b128 v[120:123], v246 offset:64
	ds_read_b128 v[124:127], v246 offset:96
	ds_read_b128 v[128:131], v246 offset:4608
	ds_read_b128 v[132:135], v246 offset:4640
	ds_read_b128 v[136:139], v246 offset:4672
	ds_read_b128 v[140:143], v246 offset:4704
	s_waitcnt lgkmcnt(0)
	v_mfma_f32_32x32x16_bf16 v[48:63], v[72:75], v[104:107], 0
	v_mfma_f32_32x32x16_bf16 v[32:47], v[72:75], v[128:131], 0
	v_mfma_f32_32x32x16_bf16 v[16:31], v[88:91], v[104:107], 0
	v_mfma_f32_32x32x16_bf16 v[0:15], v[88:91], v[128:131], 0
	v_mfma_f32_32x32x16_bf16 v[48:63], v[76:79], v[116:119], v[48:63]
	v_mfma_f32_32x32x16_bf16 v[32:47], v[76:79], v[132:135], v[32:47]
	v_mfma_f32_32x32x16_bf16 v[16:31], v[92:95], v[116:119], v[16:31]
	v_mfma_f32_32x32x16_bf16 v[0:15], v[92:95], v[132:135], v[0:15]
	v_mfma_f32_32x32x16_bf16 v[48:63], v[80:83], v[120:123], v[48:63]
	v_mfma_f32_32x32x16_bf16 v[32:47], v[80:83], v[136:139], v[32:47]
	v_mfma_f32_32x32x16_bf16 v[16:31], v[96:99], v[120:123], v[16:31]
	v_mfma_f32_32x32x16_bf16 v[0:15], v[96:99], v[136:139], v[0:15]
	v_mfma_f32_32x32x16_bf16 v[48:63], v[84:87], v[124:127], v[48:63]
	v_mfma_f32_32x32x16_bf16 v[32:47], v[84:87], v[140:143], v[32:47]
	v_mfma_f32_32x32x16_bf16 v[16:31], v[100:103], v[124:127], v[16:31]
	v_mfma_f32_32x32x16_bf16 v[0:15], v[100:103], v[140:143], v[0:15]
	s_waitcnt vmcnt(8) lgkmcnt(0)
	ds_write_b128 v245, v[144:147]
	ds_write_b128 v245, v[148:151] offset:1152
	ds_write_b128 v245, v[152:155] offset:2304
	ds_write_b128 v245, v[156:159] offset:3456
	ds_write_b128 v245, v[160:163] offset:4608
	ds_write_b128 v245, v[164:167] offset:5760
	ds_write_b128 v245, v[168:171] offset:6912
	ds_write_b128 v245, v[172:175] offset:8064
	s_waitcnt lgkmcnt(0)
	ds_read_b128 v[144:147], v246
	ds_read_b128 v[148:151], v246 offset:32
	ds_read_b128 v[152:155], v246 offset:64
	ds_read_b128 v[156:159], v246 offset:96
	ds_read_b128 v[160:163], v246 offset:4608
	ds_read_b128 v[164:167], v246 offset:4640
	ds_read_b128 v[168:171], v246 offset:4672
	ds_read_b128 v[172:175], v246 offset:4704
	s_waitcnt vmcnt(0) lgkmcnt(0)
	ds_write_b128 v245, v[176:179]
	ds_write_b128 v245, v[180:183] offset:1152
	ds_write_b128 v245, v[184:187] offset:2304
	ds_write_b128 v245, v[188:191] offset:3456
	ds_write_b128 v245, v[192:195] offset:4608
	ds_write_b128 v245, v[196:199] offset:5760
	ds_write_b128 v245, v[200:203] offset:6912
	ds_write_b128 v245, v[204:207] offset:8064
	s_waitcnt lgkmcnt(0)
	ds_read_b128 v[176:179], v246
	ds_read_b128 v[180:183], v246 offset:32
	ds_read_b128 v[184:187], v246 offset:64
	ds_read_b128 v[188:191], v246 offset:96
	ds_read_b128 v[192:195], v246 offset:4608
	ds_read_b128 v[196:199], v246 offset:4640
	ds_read_b128 v[200:203], v246 offset:4672
	ds_read_b128 v[204:207], v246 offset:4704
	s_waitcnt lgkmcnt(0)
; DI f32x16 mfma32(bf16x8 a, bf16x8 b, f32x16 c) { return __builtin_amdgcn_mfma_f32_32x32x16_bf16(a, b, c, 0, 0, 0); }
; template <int EPI, int K, int LNI>
; DI void gemm_tail_unit(const Params& p, const bf16_t* __restrict__ A, const bf16_t* __restrict__ Bt, const int un, float* s_aux) {
;     ...
; #pragma unroll 8
;     for (int s = 0; s < KS / 16; ++s) {
;         const bf16x8 a0 = *(const bf16x8*)(ap + s * 16), a1 = *(const bf16x8*)(ap + (size_t)32 * K + s * 16);
;         const bf16x8 b0 = *(const bf16x8*)(bp + s * 16), b1 = *(const bf16x8*)(bp + (size_t)32 * K + s * 16);
;         acc[0][0] = mfma32(a0, b0, acc[0][0]); acc[0][1] = mfma32(a0, b1, acc[0][1]);
;         acc[1][0] = mfma32(a1, b0, acc[1][0]); acc[1][1] = mfma32(a1, b1, acc[1][1]);
;     }
;     float* red = (float*)dsm;
; #pragma unroll
;     for (int i = 0; i < 2; ++i)
; #pragma unroll
;         for (int j = 0; j < 2; ++j)
; #pragma unroll
;             for (int reg = 0; reg < 16; ++reg) red[((w * 4 + i * 2 + j) * 16 + reg) * 64 + lane] = acc[i][j][reg];
;     __syncthreads();
;     {
;         const int tile = w >> 1, i = tile >> 1, j = tile & 1;
; #pragma unroll
;         for (int gg = 0; gg < 2; ++gg) {
;             const int g = 2 * (w & 1) + gg;
;             float v[4];
; #pragma unroll
;             for (int e = 0; e < 4; ++e) {
;                 float sacc = 0.f;
; #pragma unroll
;                 for (int wv = 0; wv < 8; ++wv) sacc += red[((wv * 4 + tile) * 16 + 4 * g + e) * 64 + lane];
	v_mfma_f32_32x32x16_bf16 v[48:63], v[144:147], v[176:179], v[48:63]
	v_mfma_f32_32x32x16_bf16 v[32:47], v[144:147], v[192:195], v[32:47]
	v_mfma_f32_32x32x16_bf16 v[16:31], v[160:163], v[176:179], v[16:31]
	v_mfma_f32_32x32x16_bf16 v[0:15], v[160:163], v[192:195], v[0:15]
	v_mfma_f32_32x32x16_bf16 v[48:63], v[148:151], v[180:183], v[48:63]
	v_mfma_f32_32x32x16_bf16 v[32:47], v[148:151], v[196:199], v[32:47]
	v_mfma_f32_32x32x16_bf16 v[16:31], v[164:167], v[180:183], v[16:31]
	v_mfma_f32_32x32x16_bf16 v[0:15], v[164:167], v[196:199], v[0:15]
	v_mfma_f32_32x32x16_bf16 v[48:63], v[152:155], v[184:187], v[48:63]
	v_mfma_f32_32x32x16_bf16 v[32:47], v[152:155], v[200:203], v[32:47]
	v_mfma_f32_32x32x16_bf16 v[16:31], v[168:171], v[184:187], v[16:31]
	v_mfma_f32_32x32x16_bf16 v[0:15], v[168:171], v[200:203], v[0:15]
	v_mfma_f32_32x32x16_bf16 v[48:63], v[156:159], v[188:191], v[48:63]
	v_mfma_f32_32x32x16_bf16 v[32:47], v[156:159], v[204:207], v[32:47]
	v_mfma_f32_32x32x16_bf16 v[16:31], v[172:175], v[188:191], v[16:31]
	v_mfma_f32_32x32x16_bf16 v[0:15], v[172:175], v[204:207], v[0:15]
	s_nop 7
	s_nop 3
	s_cmp_lt_i32 s19, 5
	ds_write2st64_b32 v64, v48, v49 offset1:1
	ds_write2st64_b32 v64, v50, v51 offset0:2 offset1:3
	ds_write2st64_b32 v64, v52, v53 offset0:4 offset1:5
	ds_write2st64_b32 v64, v54, v55 offset0:6 offset1:7
	ds_write2st64_b32 v64, v56, v57 offset0:8 offset1:9
	ds_write2st64_b32 v64, v58, v59 offset0:10 offset1:11
	ds_write2st64_b32 v64, v60, v61 offset0:12 offset1:13
	ds_write2st64_b32 v64, v62, v63 offset0:14 offset1:15
	ds_write2st64_b32 v64, v32, v33 offset0:16 offset1:17
	ds_write2st64_b32 v64, v34, v35 offset0:18 offset1:19
	v_add_u32_e32 v32, 0x10000, v69
	v_add_u32_e32 v33, 0x14000, v69
	v_add_u32_e32 v34, 0x18000, v69
	v_add_u32_e32 v35, 0x1c000, v69
	ds_write2st64_b32 v64, v36, v37 offset0:20 offset1:21
	ds_write2st64_b32 v64, v38, v39 offset0:22 offset1:23
	ds_write2st64_b32 v64, v40, v41 offset0:24 offset1:25
	ds_write2st64_b32 v64, v42, v43 offset0:26 offset1:27
	ds_write2st64_b32 v64, v44, v45 offset0:28 offset1:29
	ds_write2st64_b32 v64, v46, v47 offset0:30 offset1:31
	ds_write2st64_b32 v64, v16, v17 offset0:32 offset1:33
	ds_write2st64_b32 v64, v18, v19 offset0:34 offset1:35
	ds_write2st64_b32 v64, v20, v21 offset0:36 offset1:37
	ds_write2st64_b32 v64, v22, v23 offset0:38 offset1:39
	ds_write2st64_b32 v64, v24, v25 offset0:40 offset1:41
	ds_write2st64_b32 v64, v26, v27 offset0:42 offset1:43
	ds_write2st64_b32 v64, v28, v29 offset0:44 offset1:45
	ds_write2st64_b32 v64, v30, v31 offset0:46 offset1:47
	s_nop 11
	ds_write2st64_b32 v64, v0, v1 offset0:48 offset1:49
	ds_write2st64_b32 v64, v2, v3 offset0:50 offset1:51
	ds_write2st64_b32 v64, v4, v5 offset0:52 offset1:53
	ds_write2st64_b32 v64, v6, v7 offset0:54 offset1:55
	ds_write2st64_b32 v64, v8, v9 offset0:56 offset1:57
	ds_write2st64_b32 v64, v10, v11 offset0:58 offset1:59
	ds_write2st64_b32 v64, v12, v13 offset0:60 offset1:61
	ds_write2st64_b32 v64, v14, v15 offset0:62 offset1:63
	v_ashrrev_i32_e32 v36, 7, v67
	v_lshlrev_b32_e32 v0, 1, v70
	v_and_b32_e32 v38, 2, v0
	v_lshlrev_b32_e32 v39, 12, v36
	v_lshl_or_b32 v16, v38, 10, v39
	v_add_u32_e32 v14, v69, v16
	v_add_u32_e32 v0, v32, v16
	v_add_u32_e32 v1, v33, v16
	v_add_u32_e32 v2, v34, v16
	v_add_u32_e32 v3, v35, v16
	v_or_b32_e32 v4, 0x100, v16
	v_or_b32_e32 v17, 0x200, v16
	v_or_b32_e32 v16, 0x300, v16
	v_add_u32_e32 v5, v32, v4
	v_add_u32_e32 v6, v33, v4
	v_add_u32_e32 v7, v34, v4
	v_add_u32_e32 v10, v35, v4
	v_add_u32_e32 v18, v32, v17
	v_add_u32_e32 v19, v33, v17
	v_add_u32_e32 v21, v34, v17
	v_add_u32_e32 v17, v35, v17
	v_add_u32_e32 v23, v32, v16
	s_waitcnt lgkmcnt(0)
	s_barrier
	ds_read_b32 v8, v0
	ds_read_b32 v4, v1
	ds_read_b32 v2, v2
	ds_read_b32 v0, v3
	ds_read_b32 v9, v5
	ds_read_b32 v5, v6
	ds_read_b32 v3, v7
	ds_read_b32 v1, v10
	ds_read2st64_b32 v[28:29], v14 offset1:1
	ds_read2st64_b32 v[24:25], v14 offset0:64 offset1:65
	ds_read2st64_b32 v[6:7], v14 offset0:66 offset1:67
	ds_read2st64_b32 v[12:13], v14 offset0:2 offset1:3
	ds_read2st64_b32 v[30:31], v14 offset0:128 offset1:129
	ds_read2st64_b32 v[26:27], v14 offset0:192 offset1:193
	ds_read2st64_b32 v[10:11], v14 offset0:194 offset1:195
	ds_read2st64_b32 v[14:15], v14 offset0:130 offset1:131
	v_add_u32_e32 v37, v33, v16
	v_add_u32_e32 v40, v34, v16
	v_add_u32_e32 v41, v35, v16
	ds_read_b32 v22, v18
	ds_read_b32 v20, v19
	ds_read_b32 v18, v21
	ds_read_b32 v16, v17
	ds_read_b32 v23, v23
	ds_read_b32 v21, v37
	ds_read_b32 v19, v40
	ds_read_b32 v17, v41
	s_cbranch_scc1 .LBB0_404
	s_cmp_lg_u32 s19, 5
	s_mov_b64 s[4:5], -1
	s_cselect_b64 s[6:7], -1, 0
	s_cbranch_execz .LBB0_405
	s_branch .LBB0_406

; DI f32x16 mfma32(bf16x8 a, bf16x8 b, f32x16 c) { return __builtin_amdgcn_mfma_f32_32x32x16_bf16(a, b, c, 0, 0, 0); }
; DI f32x16 zero16() { f32x16 z; for (int i = 0; i < 16; ++i) z[i] = 0.f; return z; }
; DI int opaque_tid() { int t = threadIdx.x; asm volatile("" : "+v"(t)); return t; }
; template <int EPI, int K, int LNI>
; DI void gemm_tail_unit(const Params& p, const bf16_t* __restrict__ A, const bf16_t* __restrict__ Bt, const int un, float* s_aux) {
;     const int tid = opaque_tid(), lane = tid & 63, w = tid >> 6, r = lane & 31, h = lane >> 5;
;     constexpr int ROW0 = 32768, KS = K / 8;
;     const int col0 = un * 64;
;     if (EPI == EPI_E5B) {
;         if (tid < 64) {
;             const int hd = col0 >> 9;
;             const float* pp = (const float*)((unsigned char*)p.out + OFFO_PART) + (size_t)(ROW0 + tid) * 256 + hd * 64;
;             float sacc = 0.f;
; #pragma unroll
;             for (int i = 0; i < 16; ++i) { const f32x4 v = *(const f32x4*)(pp + i * 4); sacc += (v[0] + v[1]) + (v[2] + v[3]); }
;             s_aux[tid] = __frsqrt_rn(sacc * (1.0f / 512.0f) + 1e-6f);
;         }
;     }
;     f32x16 acc[2][2];
;     acc[0][0] = zero16(); acc[0][1] = zero16(); acc[1][0] = zero16(); acc[1][1] = zero16();
;     const bf16_t* ap = A + (size_t)(ROW0 + r) * K + w * KS + h * 8;
;     const bf16_t* bp = Bt + (size_t)(col0 + r) * K + w * KS + h * 8;
; #pragma unroll 8
;     for (int s = 0; s < KS / 16; ++s) {
;         const bf16x8 a0 = *(const bf16x8*)(ap + s * 16), a1 = *(const bf16x8*)(ap + (size_t)32 * K + s * 16);
;         const bf16x8 b0 = *(const bf16x8*)(bp + s * 16), b1 = *(const bf16x8*)(bp + (size_t)32 * K + s * 16);
;         acc[0][0] = mfma32(a0, b0, acc[0][0]); acc[0][1] = mfma32(a0, b1, acc[0][1]);
;         acc[1][0] = mfma32(a1, b0, acc[1][0]); acc[1][1] = mfma32(a1, b1, acc[1][1]);
;     }
.LBB0_1409:
	v_mov_b32_e32 v69, v210
	s_bfe_u32 s6, s50, 0x20002
	v_ashrrev_i32_e32 v116, 6, v69
	v_and_b32_e32 v68, 31, v69
	v_lshlrev_b32_e32 v2, 7, v116
	v_lshlrev_b32_e32 v64, 11, v68
	v_ashrrev_i32_e32 v3, 31, v2
	v_bfe_u32 v117, v69, 5, 1
	v_lshl_add_u64 v[0:1], s[40:41], 0, v[64:65]
	v_lshlrev_b64 v[4:5], 1, v[2:3]
	v_lshl_add_u64 v[0:1], v[0:1], 0, v[4:5]
	v_lshlrev_b32_e32 v64, 4, v117
	v_add_u32_e32 v108, s3, v68
	v_lshl_add_u64 v[12:13], v[0:1], 0, v[64:65]
	v_ashrrev_i32_e32 v109, 31, v108
	v_lshlrev_b64 v[6:7], 11, v[108:109]
	v_add_co_u32_e32 v0, vcc, s28, v12
	v_lshl_add_u64 v[6:7], s[26:27], 0, v[6:7]
	s_nop 0
	v_addc_co_u32_e32 v1, vcc, 0, v13, vcc
	s_nop 0
	v_readfirstlane_b32 s88, v0
	v_readfirstlane_b32 s89, v1
	v_lshl_add_u64 v[4:5], v[6:7], 0, v[4:5]
	v_lshl_add_u64 v[70:71], v[4:5], 0, v[64:65]
	v_add_co_u32_e32 v112, vcc, s35, v70
	v_lshl_add_u64 v[110:111], v[12:13], 0, s[8:9]
	s_nop 0
	v_addc_co_u32_e32 v113, vcc, 0, v71, vcc
	s_nop 0
	v_readfirstlane_b32 s90, v70
	v_readfirstlane_b32 s91, v71
	v_add_co_u32_e32 v114, vcc, s29, v12
	v_and_b32_e32 v64, 63, v69
	s_nop 0
	v_addc_co_u32_e32 v115, vcc, 0, v13, vcc
	v_lshl_add_u32 v70, v64, 2, 0
	v_lshl_add_u32 v64, v116, 14, v70
	s_nop 11
	s_nop 6
	s_nop 5
	v_and_b32_e32 v244, 63, v210
	v_lshrrev_b32_e32 v245, 3, v244
	v_and_b32_e32 v249, 7, v244
	v_lshlrev_b32_e32 v247, 11, v245
	v_lshl_add_u32 v247, v249, 4, v247
	v_lshrrev_b32_e32 v248, 6, v210
	v_lshlrev_b32_e32 v248, 14, v248
	v_mul_u32_u24_e32 v245, 0x90, v245
	v_lshl_add_u32 v245, v249, 4, v245
	v_add_u32_e32 v245, v245, v248
	v_and_b32_e32 v246, 31, v210
	v_mul_u32_u24_e32 v246, 0x90, v246
	v_bfe_u32 v249, v210, 5, 1
	v_lshl_add_u32 v246, v249, 4, v246
	v_add_u32_e32 v246, v246, v248
	global_load_dwordx4 v[72:75], v247, s[88:89]
	s_add_u32 s92, s88, 0x4000
	s_addc_u32 s93, s89, 0
	s_nop 0
	global_load_dwordx4 v[76:79], v247, s[92:93]
	s_add_u32 s94, s88, 0x8000
	s_addc_u32 s95, s89, 0
	s_nop 0
	global_load_dwordx4 v[80:83], v247, s[94:95]
	s_add_u32 s92, s88, 0xc000
	s_addc_u32 s93, s89, 0
	s_nop 0
	global_load_dwordx4 v[84:87], v247, s[92:93]
	s_add_u32 s94, s88, 0x10000
	s_addc_u32 s95, s89, 0
	s_nop 0
	global_load_dwordx4 v[88:91], v247, s[94:95]
	s_add_u32 s92, s88, 0x14000
	s_addc_u32 s93, s89, 0
	s_nop 0
	global_load_dwordx4 v[92:95], v247, s[92:93]
	s_add_u32 s94, s88, 0x18000
	s_addc_u32 s95, s89, 0
	s_nop 0
	global_load_dwordx4 v[96:99], v247, s[94:95]
	s_add_u32 s92, s88, 0x1c000
	s_addc_u32 s93, s89, 0
	s_nop 0
	global_load_dwordx4 v[100:103], v247, s[92:93]
	global_load_dwordx4 v[104:107], v247, s[90:91]
	s_add_u32 s94, s90, 0x4000
	s_addc_u32 s95, s91, 0
	s_nop 0
	global_load_dwordx4 v[120:123], v247, s[94:95]
	s_add_u32 s92, s90, 0x8000
	s_addc_u32 s93, s91, 0
	s_nop 0
	global_load_dwordx4 v[124:127], v247, s[92:93]
	s_add_u32 s94, s90, 0xc000
	s_addc_u32 s95, s91, 0
	s_nop 0
	global_load_dwordx4 v[128:131], v247, s[94:95]
	s_add_u32 s92, s90, 0x10000
	s_addc_u32 s93, s91, 0
	s_nop 0
	global_load_dwordx4 v[132:135], v247, s[92:93]
	s_add_u32 s94, s90, 0x14000
	s_addc_u32 s95, s91, 0
	s_nop 0
	global_load_dwordx4 v[136:139], v247, s[94:95]
	s_add_u32 s92, s90, 0x18000
	s_addc_u32 s93, s91, 0
	s_nop 0
	global_load_dwordx4 v[140:143], v247, s[92:93]
	s_add_u32 s94, s90, 0x1c000
	s_addc_u32 s95, s91, 0
	s_nop 0
	global_load_dwordx4 v[144:147], v247, s[94:95]
	global_load_dwordx4 v[148:151], v247, s[88:89] offset:128
	s_add_u32 s92, s88, 0x4000
	s_addc_u32 s93, s89, 0
	s_nop 0
	global_load_dwordx4 v[152:155], v247, s[92:93] offset:128
	s_add_u32 s94, s88, 0x8000
	s_addc_u32 s95, s89, 0
	s_nop 0
	global_load_dwordx4 v[156:159], v247, s[94:95] offset:128
	s_add_u32 s92, s88, 0xc000
	s_addc_u32 s93, s89, 0
	s_nop 0
	global_load_dwordx4 v[160:163], v247, s[92:93] offset:128
	s_add_u32 s94, s88, 0x10000
	s_addc_u32 s95, s89, 0
	s_nop 0
	global_load_dwordx4 v[164:167], v247, s[94:95] offset:128
	s_add_u32 s92, s88, 0x14000
	s_addc_u32 s93, s89, 0
	s_nop 0
	global_load_dwordx4 v[168:171], v247, s[92:93] offset:128
	s_add_u32 s94, s88, 0x18000
	s_addc_u32 s95, s89, 0
	s_nop 0
	global_load_dwordx4 v[172:175], v247, s[94:95] offset:128
	s_add_u32 s92, s88, 0x1c000
	s_addc_u32 s93, s89, 0
	s_nop 0
	global_load_dwordx4 v[176:179], v247, s[92:93] offset:128
	global_load_dwordx4 v[180:183], v247, s[90:91] offset:128
	s_add_u32 s94, s90, 0x4000
	s_addc_u32 s95, s91, 0
	s_nop 0
	global_load_dwordx4 v[184:187], v247, s[94:95] offset:128
	s_add_u32 s92, s90, 0x8000
	s_addc_u32 s93, s91, 0
	s_nop 0
	global_load_dwordx4 v[188:191], v247, s[92:93] offset:128
	s_add_u32 s94, s90, 0xc000
	s_addc_u32 s95, s91, 0
	s_nop 0
	global_load_dwordx4 v[192:195], v247, s[94:95] offset:128
	s_add_u32 s92, s90, 0x10000
	s_addc_u32 s93, s91, 0
	s_nop 0
	global_load_dwordx4 v[196:199], v247, s[92:93] offset:128
	s_add_u32 s94, s90, 0x14000
	s_addc_u32 s95, s91, 0
	s_nop 0
	global_load_dwordx4 v[200:203], v247, s[94:95] offset:128
	s_add_u32 s92, s90, 0x18000
	s_addc_u32 s93, s91, 0
	s_nop 0
	global_load_dwordx4 v[204:207], v247, s[92:93] offset:128
	s_add_u32 s94, s90, 0x1c000
	s_addc_u32 s95, s91, 0
	s_nop 0
	global_load_dwordx4 v[212:215], v247, s[94:95] offset:128
	s_waitcnt vmcnt(24) lgkmcnt(0)
	ds_write_b128 v245, v[72:75]
	ds_write_b128 v245, v[76:79] offset:1152
	ds_write_b128 v245, v[80:83] offset:2304
	ds_write_b128 v245, v[84:87] offset:3456
	ds_write_b128 v245, v[88:91] offset:4608
	ds_write_b128 v245, v[92:95] offset:5760
	ds_write_b128 v245, v[96:99] offset:6912
	ds_write_b128 v245, v[100:103] offset:8064
	s_waitcnt lgkmcnt(0)
; DI f32x16 mfma32(bf16x8 a, bf16x8 b, f32x16 c) { return __builtin_amdgcn_mfma_f32_32x32x16_bf16(a, b, c, 0, 0, 0); }
; template <int EPI, int K, int LNI>
; DI void gemm_tail_unit(const Params& p, const bf16_t* __restrict__ A, const bf16_t* __restrict__ Bt, const int un, float* s_aux) {
;     ...
; #pragma unroll 8
;     for (int s = 0; s < KS / 16; ++s) {
;         const bf16x8 a0 = *(const bf16x8*)(ap + s * 16), a1 = *(const bf16x8*)(ap + (size_t)32 * K + s * 16);
;         const bf16x8 b0 = *(const bf16x8*)(bp + s * 16), b1 = *(const bf16x8*)(bp + (size_t)32 * K + s * 16);
;         acc[0][0] = mfma32(a0, b0, acc[0][0]); acc[0][1] = mfma32(a0, b1, acc[0][1]);
;         acc[1][0] = mfma32(a1, b0, acc[1][0]); acc[1][1] = mfma32(a1, b1, acc[1][1]);
;     }
;     float* red = (float*)dsm;
; #pragma unroll
;     for (int i = 0; i < 2; ++i)
; #pragma unroll
;         for (int j = 0; j < 2; ++j)
; #pragma unroll
;             for (int reg = 0; reg < 16; ++reg) red[((w * 4 + i * 2 + j) * 16 + reg) * 64 + lane] = acc[i][j][reg];
	ds_read_b128 v[72:75], v246
	ds_read_b128 v[76:79], v246 offset:32
	ds_read_b128 v[80:83], v246 offset:64
	ds_read_b128 v[84:87], v246 offset:96
	ds_read_b128 v[88:91], v246 offset:4608
	ds_read_b128 v[92:95], v246 offset:4640
	ds_read_b128 v[96:99], v246 offset:4672
	ds_read_b128 v[100:103], v246 offset:4704
	s_waitcnt vmcnt(16) lgkmcnt(0)
	ds_write_b128 v245, v[104:107]
	ds_write_b128 v245, v[120:123] offset:1152
	ds_write_b128 v245, v[124:127] offset:2304
	ds_write_b128 v245, v[128:131] offset:3456
	ds_write_b128 v245, v[132:135] offset:4608
	ds_write_b128 v245, v[136:139] offset:5760
	ds_write_b128 v245, v[140:143] offset:6912
	ds_write_b128 v245, v[144:147] offset:8064
	s_waitcnt lgkmcnt(0)
	ds_read_b128 v[104:107], v246
	ds_read_b128 v[120:123], v246 offset:32
	ds_read_b128 v[124:127], v246 offset:64
	ds_read_b128 v[128:131], v246 offset:96
	ds_read_b128 v[132:135], v246 offset:4608
	ds_read_b128 v[136:139], v246 offset:4640
	ds_read_b128 v[140:143], v246 offset:4672
	ds_read_b128 v[144:147], v246 offset:4704
	s_waitcnt lgkmcnt(0)
	v_mfma_f32_32x32x16_bf16 v[48:63], v[72:75], v[104:107], 0
	v_mfma_f32_32x32x16_bf16 v[32:47], v[72:75], v[132:135], 0
	v_mfma_f32_32x32x16_bf16 v[16:31], v[88:91], v[104:107], 0
	v_mfma_f32_32x32x16_bf16 v[0:15], v[88:91], v[132:135], 0
	v_mfma_f32_32x32x16_bf16 v[48:63], v[76:79], v[120:123], v[48:63]
	v_mfma_f32_32x32x16_bf16 v[32:47], v[76:79], v[136:139], v[32:47]
	v_mfma_f32_32x32x16_bf16 v[16:31], v[92:95], v[120:123], v[16:31]
	v_mfma_f32_32x32x16_bf16 v[0:15], v[92:95], v[136:139], v[0:15]
	v_mfma_f32_32x32x16_bf16 v[48:63], v[80:83], v[124:127], v[48:63]
	v_mfma_f32_32x32x16_bf16 v[32:47], v[80:83], v[140:143], v[32:47]
	v_mfma_f32_32x32x16_bf16 v[16:31], v[96:99], v[124:127], v[16:31]
	v_mfma_f32_32x32x16_bf16 v[0:15], v[96:99], v[140:143], v[0:15]
	v_mfma_f32_32x32x16_bf16 v[48:63], v[84:87], v[128:131], v[48:63]
	v_mfma_f32_32x32x16_bf16 v[32:47], v[84:87], v[144:147], v[32:47]
	v_mfma_f32_32x32x16_bf16 v[16:31], v[100:103], v[128:131], v[16:31]
	v_mfma_f32_32x32x16_bf16 v[0:15], v[100:103], v[144:147], v[0:15]
	s_waitcnt vmcnt(8) lgkmcnt(0)
	ds_write_b128 v245, v[148:151]
	ds_write_b128 v245, v[152:155] offset:1152
	ds_write_b128 v245, v[156:159] offset:2304
	ds_write_b128 v245, v[160:163] offset:3456
	ds_write_b128 v245, v[164:167] offset:4608
	ds_write_b128 v245, v[168:171] offset:5760
	ds_write_b128 v245, v[172:175] offset:6912
	ds_write_b128 v245, v[176:179] offset:8064
	s_waitcnt lgkmcnt(0)
	ds_read_b128 v[148:151], v246
	ds_read_b128 v[152:155], v246 offset:32
	ds_read_b128 v[156:159], v246 offset:64
	ds_read_b128 v[160:163], v246 offset:96
	ds_read_b128 v[164:167], v246 offset:4608
	ds_read_b128 v[168:171], v246 offset:4640
	ds_read_b128 v[172:175], v246 offset:4672
	ds_read_b128 v[176:179], v246 offset:4704
	s_waitcnt vmcnt(0) lgkmcnt(0)
	ds_write_b128 v245, v[180:183]
	ds_write_b128 v245, v[184:187] offset:1152
	ds_write_b128 v245, v[188:191] offset:2304
	ds_write_b128 v245, v[192:195] offset:3456
	ds_write_b128 v245, v[196:199] offset:4608
	ds_write_b128 v245, v[200:203] offset:5760
	ds_write_b128 v245, v[204:207] offset:6912
	ds_write_b128 v245, v[212:215] offset:8064
	s_waitcnt lgkmcnt(0)
	ds_read_b128 v[180:183], v246
	ds_read_b128 v[184:187], v246 offset:32
	ds_read_b128 v[188:191], v246 offset:64
	ds_read_b128 v[192:195], v246 offset:96
	ds_read_b128 v[196:199], v246 offset:4608
	ds_read_b128 v[200:203], v246 offset:4640
	ds_read_b128 v[204:207], v246 offset:4672
	ds_read_b128 v[212:215], v246 offset:4704
	s_waitcnt lgkmcnt(0)
	v_mfma_f32_32x32x16_bf16 v[48:63], v[148:151], v[180:183], v[48:63]
	v_mfma_f32_32x32x16_bf16 v[32:47], v[148:151], v[196:199], v[32:47]
	v_mfma_f32_32x32x16_bf16 v[16:31], v[164:167], v[180:183], v[16:31]
	v_mfma_f32_32x32x16_bf16 v[0:15], v[164:167], v[196:199], v[0:15]
	v_mfma_f32_32x32x16_bf16 v[48:63], v[152:155], v[184:187], v[48:63]
	v_mfma_f32_32x32x16_bf16 v[32:47], v[152:155], v[200:203], v[32:47]
	v_mfma_f32_32x32x16_bf16 v[16:31], v[168:171], v[184:187], v[16:31]
	v_mfma_f32_32x32x16_bf16 v[0:15], v[168:171], v[200:203], v[0:15]
	v_mfma_f32_32x32x16_bf16 v[48:63], v[156:159], v[188:191], v[48:63]
	v_mfma_f32_32x32x16_bf16 v[32:47], v[156:159], v[204:207], v[32:47]
	v_mfma_f32_32x32x16_bf16 v[16:31], v[172:175], v[188:191], v[16:31]
	v_mfma_f32_32x32x16_bf16 v[0:15], v[172:175], v[204:207], v[0:15]
	v_mfma_f32_32x32x16_bf16 v[48:63], v[160:163], v[192:195], v[48:63]
	v_mfma_f32_32x32x16_bf16 v[32:47], v[160:163], v[212:215], v[32:47]
	v_mfma_f32_32x32x16_bf16 v[16:31], v[176:179], v[192:195], v[16:31]
	v_mfma_f32_32x32x16_bf16 v[0:15], v[176:179], v[212:215], v[0:15]
	s_nop 7
	s_nop 3
	ds_write2st64_b32 v64, v48, v49 offset1:1
	ds_write2st64_b32 v64, v50, v51 offset0:2 offset1:3
	ds_write2st64_b32 v64, v52, v53 offset0:4 offset1:5
	ds_write2st64_b32 v64, v54, v55 offset0:6 offset1:7
	ds_write2st64_b32 v64, v56, v57 offset0:8 offset1:9
	ds_write2st64_b32 v64, v58, v59 offset0:10 offset1:11
	ds_write2st64_b32 v64, v60, v61 offset0:12 offset1:13
	ds_write2st64_b32 v64, v62, v63 offset0:14 offset1:15
	ds_write2st64_b32 v64, v32, v33 offset0:16 offset1:17
	ds_write2st64_b32 v64, v34, v35 offset0:18 offset1:19
	ds_write2st64_b32 v64, v36, v37 offset0:20 offset1:21
	ds_write2st64_b32 v64, v38, v39 offset0:22 offset1:23
	ds_write2st64_b32 v64, v40, v41 offset0:24 offset1:25
	ds_write2st64_b32 v64, v42, v43 offset0:26 offset1:27
	ds_write2st64_b32 v64, v44, v45 offset0:28 offset1:29
	ds_write2st64_b32 v64, v46, v47 offset0:30 offset1:31
	ds_write2st64_b32 v64, v16, v17 offset0:32 offset1:33
;     ...
;     } else if (EPI == EPI_E5) {
;         const int idx = (pos + 48) & 63, ch = (pos + 48) >> 6;
;         if (col < 1024) {
;             const int hd = col >> 8, item = (ch * 4 + b) * 4 + hd;
;             bf16_t* d = (bf16_t*)((unsigned char*)p.out + OFFO_QHAT) + qf_off(item, idx, col & 255);
; #pragma unroll
;             for (int e = 0; e < 4; ++e) d[e * 8] = f2bf(v[e] * rs[e][0]);
;         } else if (col < 2048) {
;             const int c = col - 1024, hd = c >> 8, item = (ch * 4 + b) * 4 + hd;
;             bf16_t* d = (bf16_t*)(p.ws + OFF_KHAT) + (size_t)row0 * 1024 + c;
; #pragma unroll
;             for (int e = 0; e < 4; ++e) { v[e] *= rs[e][1]; d[(size_t)e * 1024] = f2bf(v[e]); }
;             u32x2 wv; wv[0] = cvt_pk(v[0], v[1]); wv[1] = cvt_pk(v[2], v[3]);
;             *(u32x2*)((bf16_t*)(p.ws + OFF_KHATT) + kf_off(item, c & 255, idx)) = wv;
;         } else {
;             const int c = col - 2048, hd = c >> 9, item = (ch * 4 + b) * 4 + hd;
; template <int EPI, int K, int LNI>
; DI void gemm_tail_unit(const Params& p, const bf16_t* __restrict__ A, const bf16_t* __restrict__ Bt, const int un, float* s_aux) {
;     ...
;     float* red = (float*)dsm;
; #pragma unroll
;     for (int i = 0; i < 2; ++i)
; #pragma unroll
;         for (int j = 0; j < 2; ++j)
; #pragma unroll
;             for (int reg = 0; reg < 16; ++reg) red[((w * 4 + i * 2 + j) * 16 + reg) * 64 + lane] = acc[i][j][reg];
;     __syncthreads();
;     {
;         const int tile = w >> 1, i = tile >> 1, j = tile & 1;
; #pragma unroll
;         for (int gg = 0; gg < 2; ++gg) {
;             const int g = 2 * (w & 1) + gg;
;             float v[4];
; #pragma unroll
;             for (int e = 0; e < 4; ++e) {
;                 float sacc = 0.f;
; #pragma unroll
;                 for (int wv = 0; wv < 8; ++wv) sacc += red[((wv * 4 + tile) * 16 + 4 * g + e) * 64 + lane];
;                 v[e] = sacc;
;             }
;             const int lrow0 = i * 32 + 8 * g + 4 * h;
;             f32x2 rs[4]; float lng = 1.f, lnb = 0.f;
;             if (EPI == EPI_E5) {
;                 lng = log2f(1.f - ex2(-5.f - (float)((col0 >> 8) & 3)));
;                 const int idx_ = (((ROW0 + lrow0) % LT) + 48) & 63;
; #pragma unroll
;                 for (int e = 0; e < 4; ++e) rs[e] = (f32x2){ex2(lng * (float)(idx_ + e + 1)), 0.0625f * ex2(lng * (float)(63 - idx_ - e))};
	ds_write2st64_b32 v64, v18, v19 offset0:34 offset1:35
	ds_write2st64_b32 v64, v20, v21 offset0:36 offset1:37
	ds_write2st64_b32 v64, v22, v23 offset0:38 offset1:39
	ds_write2st64_b32 v64, v24, v25 offset0:40 offset1:41
	ds_write2st64_b32 v64, v26, v27 offset0:42 offset1:43
	ds_write2st64_b32 v64, v28, v29 offset0:44 offset1:45
	ds_write2st64_b32 v64, v30, v31 offset0:46 offset1:47
	s_nop 11
	ds_write2st64_b32 v64, v0, v1 offset0:48 offset1:49
	ds_write2st64_b32 v64, v2, v3 offset0:50 offset1:51
	ds_write2st64_b32 v64, v4, v5 offset0:52 offset1:53
	ds_write2st64_b32 v64, v6, v7 offset0:54 offset1:55
	ds_write2st64_b32 v64, v8, v9 offset0:56 offset1:57
	ds_write2st64_b32 v64, v10, v11 offset0:58 offset1:59
	ds_write2st64_b32 v64, v12, v13 offset0:60 offset1:61
	ds_write2st64_b32 v64, v14, v15 offset0:62 offset1:63
	v_cvt_f32_ubyte0_e32 v1, s6
	v_sub_f32_e32 v1, 0xc0a00000, v1
	v_exp_f32_e32 v1, v1
	v_ashrrev_i32_e32 v0, 7, v69
	v_lshlrev_b32_e32 v2, 1, v116
	v_lshlrev_b32_e32 v17, 12, v0
	v_sub_f32_e32 v1, 1.0, v1
	v_cmp_gt_f32_e32 vcc, s43, v1
	s_and_b64 s[6:7], vcc, exec
	s_cselect_b32 s6, 32, 0
	v_ldexp_f32 v1, v1, s6
	v_log_f32_e32 v1, v1
	v_lshlrev_b32_e32 v0, 5, v0
	v_and_b32_e32 v16, 2, v2
	v_cndmask_b32_e32 v2, 0, v66, vcc
	v_and_b32_e32 v0, 32, v0
	v_sub_f32_e32 v7, v1, v2
	v_add_u32_e32 v1, s3, v0
	v_add_u32_e32 v18, v108, v0
	v_sub_co_u32_e32 v0, vcc, s3, v67
	v_lshrrev_b32_e32 v0, 3, v0
	v_and_b32_e32 v0, 0x1fffffc0, v0
	v_lshrrev_b32_e32 v1, 3, v1
	v_add_u32_e32 v64, 0xfffffc00, v18
	v_and_or_b32 v10, v1, 60, v0
	v_lshrrev_b32_e32 v0, 3, v64
	v_and_b32_e32 v1, 28, v1
	v_and_or_b32 v9, v0, s45, v1
	v_lshlrev_b32_e32 v1, 1, v69
	v_lshrrev_b32_e32 v2, 1, v69
	v_lshl_or_b32 v19, v16, 10, v17
	v_ashrrev_i32_e32 v3, 3, v69
	v_lshlrev_b32_e32 v6, 2, v117
	v_and_b32_e32 v0, 19, v69
	v_and_b32_e32 v1, 8, v1
	v_and_b32_e32 v2, 4, v2
	v_add_u32_e32 v34, v70, v19
	s_waitcnt lgkmcnt(0)
	s_barrier
	v_and_or_b32 v11, v3, s42, v6
	v_or3_b32 v8, v2, v0, v1
	ds_read2st64_b32 v[0:1], v34 offset1:1
	ds_read2st64_b32 v[2:3], v34 offset0:64 offset1:65
	ds_read2st64_b32 v[4:5], v34 offset0:128 offset1:129
	ds_read2st64_b32 v[20:21], v34 offset0:192 offset1:193
	v_add_u32_e32 v12, 0x10000, v70
	v_add_u32_e32 v13, 0x14000, v70
	v_add_u32_e32 v14, 0x18000, v70
	v_add_u32_e32 v15, 0x1c000, v70
	v_or_b32_e32 v24, 0x100, v19
	s_waitcnt lgkmcnt(3)
	v_pk_add_f32 v[0:1], v[0:1], 0 op_sel_hi:[1,0]
	v_add_u32_e32 v22, v12, v19
	v_add_u32_e32 v23, v13, v19
	v_add_u32_e32 v25, v14, v19
	v_add_u32_e32 v27, v15, v19
	v_add_u32_e32 v29, v12, v24
	v_add_u32_e32 v30, v13, v24
	v_add_u32_e32 v31, v14, v24
	v_add_u32_e32 v32, v15, v24
	s_waitcnt lgkmcnt(2)
	v_pk_add_f32 v[0:1], v[0:1], v[2:3]
	ds_read_b32 v22, v22
	ds_read_b32 v24, v23
	ds_read_b32 v26, v25
	ds_read_b32 v28, v27
	ds_read_b32 v23, v29
	ds_read_b32 v25, v30
	ds_read_b32 v27, v31
	ds_read_b32 v29, v32
	ds_read2st64_b32 v[30:31], v34 offset0:66 offset1:67
	ds_read2st64_b32 v[32:33], v34 offset0:2 offset1:3
	s_waitcnt lgkmcnt(11)
	v_pk_add_f32 v[0:1], v[0:1], v[4:5]
	ds_read2st64_b32 v[2:3], v34 offset0:194 offset1:195
	ds_read2st64_b32 v[34:35], v34 offset0:130 offset1:131
	s_waitcnt lgkmcnt(12)
	v_pk_add_f32 v[0:1], v[0:1], v[20:21]
	v_or_b32_e32 v4, 0x200, v19
	s_waitcnt lgkmcnt(7)
	v_pk_add_f32 v[0:1], v[0:1], v[22:23]
	v_add_u32_e32 v5, v12, v4
	s_waitcnt lgkmcnt(6)
	v_pk_add_f32 v[0:1], v[0:1], v[24:25]
	v_add_u32_e32 v20, v13, v4
	v_add_u32_e32 v21, v14, v4
	v_add_u32_e32 v23, v15, v4
	v_or_b32_e32 v4, 0x300, v19
	s_waitcnt lgkmcnt(5)
	v_pk_add_f32 v[0:1], v[0:1], v[26:27]
	v_add_u32_e32 v25, v13, v4
	v_add_u32_e32 v26, v14, v4
	v_add_u32_e32 v27, v15, v4
	v_add_u32_e32 v19, v12, v4
	ds_read_b32 v4, v5
	ds_read_b32 v20, v20
	ds_read_b32 v22, v21
	ds_read_b32 v24, v23
	ds_read_b32 v5, v19
	ds_read_b32 v21, v25
	ds_read_b32 v23, v26
	ds_read_b32 v25, v27
	s_waitcnt lgkmcnt(10)
	v_pk_add_f32 v[26:27], v[32:33], 0 op_sel_hi:[1,0]
	v_cmp_lt_i32_e64 s[6:7], s44, v18
	v_pk_add_f32 v[26:27], v[26:27], v[30:31]
	s_xor_b64 s[12:13], vcc, -1
	s_waitcnt lgkmcnt(8)
	v_pk_add_f32 v[26:27], v[26:27], v[34:35]
	v_pk_add_f32 v[0:1], v[0:1], v[28:29]
	v_pk_add_f32 v[2:3], v[26:27], v[2:3]
	s_waitcnt lgkmcnt(3)
	v_pk_add_f32 v[2:3], v[2:3], v[4:5]
	v_lshl_or_b32 v5, v16, 3, v11
	v_add_u32_e32 v4, 0x8000, v5
	v_mul_hi_i32 v19, v4, s46
	s_waitcnt lgkmcnt(2)
	v_pk_add_f32 v[2:3], v[2:3], v[20:21]
	v_lshrrev_b32_e32 v20, 31, v19
	v_ashrrev_i32_e32 v19, 12, v19
	v_add_u32_e32 v21, v19, v20
	v_mul_i32_i24_e32 v19, 0x2010, v21
	v_sub_u32_e32 v19, v4, v19
	v_add_u32_e32 v19, 48, v19
	s_waitcnt lgkmcnt(1)
	v_pk_add_f32 v[2:3], v[2:3], v[22:23]
	v_and_b32_e32 v23, 63, v19
	v_mul_i32_i24_e32 v19, 0xffffdff0, v21
	s_waitcnt lgkmcnt(0)
	v_pk_add_f32 v[2:3], v[2:3], v[24:25]
	v_add3_u32 v24, v5, v19, s47
	v_and_b32_e32 v20, 60, v24
	v_ashrrev_i32_e32 v22, 6, v24
	s_and_saveexec_b64 s[14:15], s[6:7]
	s_xor_b64 s[14:15], exec, s[14:15]
	s_cbranch_execz .LBB0_1414
	s_mov_b64 s[22:23], -1
	s_and_b64 vcc, exec, s[12:13]
	s_cbranch_vccz .LBB0_1412
	v_lshlrev_b32_e32 v5, 10, v22
	v_lshlrev_b32_e32 v19, 8, v21
	v_lshrrev_b32_e32 v26, 4, v20
	v_add3_u32 v5, v19, v10, v5
	v_or_b32_e32 v26, v5, v26
	v_ashrrev_i32_e32 v27, 31, v26
	v_lshlrev_b64 v[26:27], 6, v[26:27]
	v_lshlrev_b32_e32 v5, 2, v20
	v_and_or_b32 v5, v5, 32, v26
	v_or_b32_e32 v26, v5, v68
	v_lshl_add_u64 v[26:27], v[26:27], 4, s[20:21]
	v_lshlrev_b32_e32 v28, 1, v6
	v_mov_b32_e32 v29, v65
	v_cvt_pk_bf16_f32 v24, v0, v1
	v_cvt_pk_bf16_f32 v25, v2, v3
	v_lshl_add_u64 v[26:27], v[26:27], 0, v[28:29]
	global_store_dwordx2 v[26:27], v[24:25], off
	s_mov_b64 s[22:23], 0
